# deferred GEMM1 units run during the attention phase on workgroups 0-79 (other 176 share the attention/hgrn-kv units); hgrn-out phase on all 256 workgroups
# baseline (speedup 1.0000x reference)
.LBB0_459:
.LBB0_460:
	v_writelane_b32 v228, s88, 20
	s_cmp_lt_i32 s86, 3
	s_cselect_b64 s[0:1], -1, 0
	s_add_u32 s48, s82, 0x2000000
	s_addc_u32 s49, s83, 0
	s_add_u32 s50, s84, 0x40000
	s_addc_u32 s51, s85, 0
	s_and_b64 s[52:53], s[0:1], s[4:5]
	s_andn2_b64 vcc, exec, s[52:53]
	s_cbranch_vccnz .LBB0_541
	s_cmp_lg_u32 s88, 0x100
	s_cbranch_scc1 .Lp2_normal
	s_cmp_lt_u32 s94, 0x50
	s_cbranch_scc0 .Lp2_units
	s_mov_b32 s97, 1
	s_mov_b64 s[10:11], 0
	s_movk_i32 s3, 0x50
	v_and_b32_e32 v131, 63, v165
	v_and_b32_e32 v148, 15, v165
	v_lshrrev_b32_e32 v151, 2, v165
	v_lshrrev_b32_e32 v150, 3, v165
	v_bfe_u32 v149, v165, 4, 2
	v_and_b32_e32 v130, 48, v165
	s_branch .Lp4_gemm_entry
.Lp2_gemm_ret:
	s_mov_b32 s97, 0
	s_add_u32 s48, s82, 0x2000000
	s_addc_u32 s49, s83, 0
	s_add_u32 s50, s84, 0x40000
	s_addc_u32 s51, s85, 0
	s_mov_b64 s[52:53], -1
	s_branch .LBB0_541
.Lp2_units:
	s_sub_i32 s94, s94, 0x50
	s_movk_i32 s88, 0xb0
	s_nop 0
	v_writelane_b32 v228, s88, 6
.Lp2_normal:
	s_movk_i32 s0, 0x1ff
	v_cmp_lt_u32_e64 s[4:5], s0, v165
	s_movk_i32 s0, 0x1bf
	v_cmp_lt_u32_e64 s[6:7], s0, v165
	s_movk_i32 s0, 0x17f
	v_cmp_lt_u32_e64 s[8:9], s0, v165
	s_movk_i32 s0, 0x13f
	v_cmp_lt_u32_e64 s[10:11], s0, v165
	s_movk_i32 s0, 0xff
	v_lshrrev_b32_e32 v23, 6, v165
	v_cmp_lt_u32_e64 s[12:13], s0, v165
	s_movk_i32 s0, 0xbf
	v_lshlrev_b32_e32 v31, 4, v23
	v_and_b32_e32 v25, 15, v165
	v_cmp_lt_u32_e64 s[14:15], s0, v165
	s_movk_i32 s0, 0x7f
	s_cmpk_gt_i32 s94, 0x2ff
	v_lshlrev_b32_e32 v18, 3, v165
	v_lshrrev_b32_e32 v29, 3, v165
	v_or_b32_e32 v20, v31, v25
	v_cmp_lt_u32_e64 s[16:17], s0, v165
	v_lshrrev_b32_e32 v33, 2, v165
	v_lshlrev_b32_e32 v22, 1, v25
	v_cmp_lt_u32_e64 s[18:19], 63, v165
	s_cbranch_scc1 .LBB0_466
	s_waitcnt vmcnt(0)
	v_add_u32_e32 v3, 0x200, v165
	v_lshrrev_b32_e32 v5, 4, v3
	v_lshrrev_b32_e32 v3, 3, v3
	v_or_b32_e32 v4, 0x400, v165
	v_and_b32_e32 v3, 0xfe, v3
	v_and_b32_e32 v12, 0x7e, v29
	v_add_u32_e32 v36, 0xffffff80, v3
	v_lshrrev_b32_e32 v3, 3, v4
	s_movk_i32 s1, 0x1080
	v_or_b32_e32 v37, 0xffffff80, v5
	v_lshrrev_b32_e32 v6, 4, v4
	v_add_u32_e32 v7, 0x600, v165
	v_or_b32_e32 v41, 0xffffff80, v12
	v_and_b32_e32 v3, 0xfe, v3
	v_mul_u32_u24_e32 v12, 0x110, v5
	v_mad_u32_u24 v15, v25, s1, 0
	v_lshlrev_b32_e32 v17, 3, v25
	v_lshlrev_b32_e32 v5, 2, v5
	v_add_u32_e32 v38, 0xffffff80, v3
	v_lshrrev_b32_e32 v3, 3, v7
	v_add3_u32 v47, v15, v5, v17
	v_add_u32_e32 v5, v6, v22
	v_lshrrev_b32_e32 v24, 4, v165
	v_lshrrev_b32_e32 v8, 4, v7
	v_bfe_u32 v11, v165, 4, 2
	v_and_b32_e32 v3, 0x1fe, v3
	v_and_b32_e32 v5, 0x7f, v5
	v_or_b32_e32 v39, 0xffffff80, v6
	v_add_u32_e32 v40, 0xffffff80, v3
	v_lshlrev_b32_e32 v3, 4, v165
	v_mul_u32_u24_e32 v13, 0x110, v6
	v_lshlrev_b32_e32 v16, 2, v24
	v_lshl_add_u32 v48, v5, 2, v15
	v_add_u32_e32 v5, v8, v22
	v_lshlrev_b32_e32 v6, 2, v11
	v_add_u32_e32 v45, 4, v23
	v_add_u32_e32 v28, 0xffffff80, v8
	s_add_i32 s0, 0, 0x10800
	v_and_b32_e32 v3, 0xf0, v3
	v_mul_u32_u24_e32 v14, 0x110, v8
	v_add3_u32 v46, v15, v16, v17
	v_and_b32_e32 v5, 0x7f, v5
	v_add_u32_e32 v8, 0x80, v20
	v_or_b32_e32 v16, v6, v31
	v_min_u32_e32 v82, 15, v45
	v_add_u32_e32 v3, s0, v3
	v_lshl_add_u32 v49, v5, 2, v15
	v_lshl_add_u32 v5, v11, 4, s0
	v_cmp_ge_u32_e32 vcc, v6, v25
	v_cmp_le_u32_e64 s[0:1], v16, v8
	v_or_b32_e32 v17, 1, v16
	v_lshl_or_b32 v50, v82, 4, v25
	s_and_b64 s[58:59], vcc, s[0:1]
	v_cmp_ge_u32_e32 vcc, v17, v20
	v_cmp_lt_u32_e64 s[0:1], v16, v8
	v_or_b32_e32 v17, 2, v16
	v_mul_u32_u24_e32 v142, 0x110, v50
	v_min_u32_e32 v50, 10, v23
	s_and_b64 s[72:73], vcc, s[0:1]
	v_cmp_ge_u32_e32 vcc, v17, v20
	v_cmp_le_u32_e64 s[0:1], v17, v8
	v_or_b32_e32 v16, 3, v16
	v_lshl_or_b32 v50, v50, 4, v25
	v_add_u32_e32 v98, 6, v23
	s_and_b64 s[74:75], vcc, s[0:1]
	v_cmp_ge_u32_e32 vcc, v16, v20
	v_cmp_le_u32_e64 s[0:1], v16, v8
	v_add_u32_e32 v50, 0x50, v50
	v_min_u32_e32 v99, 15, v98
	s_and_b64 s[76:77], vcc, s[0:1]
	s_movk_i32 s0, 0x380
	v_mul_u32_u24_e32 v143, 0x110, v50
	v_lshl_or_b32 v50, v99, 4, v25
	v_cmp_gt_u32_e64 s[22:23], s0, v165
	s_movk_i32 s0, 0x340
	v_mul_u32_u24_e32 v144, 0x110, v50
	v_min_u32_e32 v50, 8, v23
	v_cmp_gt_u32_e64 s[24:25], s0, v165
	s_movk_i32 s0, 0x300
	v_lshl_or_b32 v50, v50, 4, v25
	v_add_u32_e32 v114, 8, v23
	v_cmp_gt_u32_e64 s[26:27], s0, v165
	s_movk_i32 s0, 0x2c0
	v_add_u32_e32 v50, 0x70, v50
	v_min_u32_e32 v115, 15, v114
	v_cmp_gt_u32_e64 s[28:29], s0, v165
	s_movk_i32 s0, 0x280
	v_mul_u32_u24_e32 v145, 0x110, v50
	v_lshl_or_b32 v50, v115, 4, v25
	v_cmp_gt_u32_e64 s[30:31], s0, v165
	s_movk_i32 s0, 0x240
	v_mul_u32_u24_e32 v146, 0x110, v50
	v_lshl_or_b32 v50, v114, 4, v6
	v_cmp_gt_u32_e64 s[34:35], s0, v165
	v_cmp_ge_u32_e32 vcc, v50, v20
	v_cmp_le_u32_e64 s[0:1], v50, v8
	v_or_b32_e32 v51, 1, v50
	s_and_b64 s[36:37], vcc, s[0:1]
	v_cmp_ge_u32_e32 vcc, v51, v20
	v_cmp_lt_u32_e64 s[0:1], v50, v8
	v_or_b32_e32 v51, 2, v50
	s_and_b64 s[38:39], vcc, s[0:1]
	v_cmp_ge_u32_e32 vcc, v51, v20
	v_cmp_le_u32_e64 s[0:1], v51, v8
	v_or_b32_e32 v50, 3, v50
	s_and_b64 s[40:41], vcc, s[0:1]
	v_cmp_le_u32_e64 s[0:1], v50, v8
	v_and_b32_e32 v8, 2, v33
	v_min_u32_e32 v16, 14, v23
	v_lshl_add_u32 v8, v11, 1, v8
	v_lshl_or_b32 v17, v16, 4, v25
	v_cmp_ge_u32_e32 vcc, v50, v20
	v_lshl_add_u32 v16, v16, 3, 8
	v_add_u32_e32 v117, 4, v8
	v_add_u32_e32 v119, 8, v8
	v_add_u32_e32 v121, 12, v8
	v_or_b32_e32 v123, 16, v8
	v_add_u32_e32 v125, 20, v8
	v_add_u32_e32 v127, 24, v8
	v_add_u32_e32 v130, 28, v8
	v_add_u32_e32 v26, 2, v23
	s_and_b64 s[42:43], vcc, s[0:1]
	s_movk_i32 s0, 0x210
	v_add_u32_e32 v51, v16, v8
	v_add_u32_e32 v53, v117, v16
	v_add_u32_e32 v55, v119, v16
	v_add_u32_e32 v57, v121, v16
	v_add_u32_e32 v59, v123, v16
	v_add_u32_e32 v61, v125, v16
	v_add_u32_e32 v63, v127, v16
	v_add_u32_e32 v16, v130, v16
	v_min_u32_e32 v42, 15, v26
	v_mad_u32_u24 v129, v25, s0, 0
	v_and_b32_e32 v16, 0x7e, v16
	v_lshl_add_u32 v65, v16, 2, v129
	v_min_u32_e32 v16, 14, v26
	v_lshlrev_b32_e32 v26, 3, v42
	v_lshl_or_b32 v43, v42, 4, v25
	v_add_u32_e32 v42, v8, v26
	v_lshl_add_u32 v16, v16, 3, 8
	v_and_b32_e32 v42, 0x7e, v42
	v_lshl_add_u32 v66, v42, 2, v129
	v_add_u32_e32 v42, v16, v8
	v_and_b32_e32 v42, 0x7e, v42
	v_lshl_add_u32 v67, v42, 2, v129
	v_add_u32_e32 v42, v117, v26
	v_and_b32_e32 v42, 0x7e, v42
	v_lshl_add_u32 v68, v42, 2, v129
	v_add_u32_e32 v42, v16, v117
	v_and_b32_e32 v42, 0x7e, v42
	v_lshl_add_u32 v69, v42, 2, v129
	v_add_u32_e32 v42, v119, v26
	v_and_b32_e32 v42, 0x7e, v42
	v_lshl_add_u32 v70, v42, 2, v129
	v_add_u32_e32 v42, v16, v119
	v_and_b32_e32 v42, 0x7e, v42
	v_lshl_add_u32 v71, v42, 2, v129
	v_add_u32_e32 v42, v121, v26
	v_and_b32_e32 v42, 0x7e, v42
	v_lshl_add_u32 v72, v42, 2, v129
	v_add_u32_e32 v42, v16, v121
	v_and_b32_e32 v42, 0x7e, v42
	v_lshl_add_u32 v73, v42, 2, v129
	v_add_u32_e32 v42, v123, v26
	v_and_b32_e32 v42, 0x7e, v42
	v_lshl_add_u32 v74, v42, 2, v129
	v_add_u32_e32 v42, v16, v123
	v_and_b32_e32 v42, 0x7e, v42
	v_lshl_add_u32 v75, v42, 2, v129
	v_add_u32_e32 v42, v125, v26
	v_and_b32_e32 v42, 0x7e, v42
	v_lshl_add_u32 v76, v42, 2, v129
	v_add_u32_e32 v42, v16, v125
	v_and_b32_e32 v42, 0x7e, v42
	v_lshl_add_u32 v77, v42, 2, v129
	v_add_u32_e32 v42, v127, v26
	v_and_b32_e32 v42, 0x7e, v42
	v_add_u32_e32 v26, v130, v26
	v_lshl_add_u32 v78, v42, 2, v129
	v_add_u32_e32 v42, v16, v127
	v_and_b32_e32 v26, 0x7e, v26
	v_add_u32_e32 v16, v16, v130
	v_and_b32_e32 v42, 0x7e, v42
	v_lshl_add_u32 v80, v26, 2, v129
	v_and_b32_e32 v16, 0x7e, v16
	v_lshlrev_b32_e32 v26, 3, v82
	v_lshl_add_u32 v79, v42, 2, v129
	v_lshl_add_u32 v81, v16, 2, v129
	v_min_u32_e32 v16, 14, v45
	v_add_u32_e32 v42, v8, v26
	v_lshl_add_u32 v16, v16, 3, 8
	v_and_b32_e32 v42, 0x7e, v42
	v_lshl_add_u32 v82, v42, 2, v129
	v_add_u32_e32 v42, v16, v8
	v_and_b32_e32 v42, 0x7e, v42
	v_lshl_add_u32 v83, v42, 2, v129
	v_add_u32_e32 v42, v117, v26
	v_and_b32_e32 v42, 0x7e, v42
	v_lshl_add_u32 v84, v42, 2, v129
	v_add_u32_e32 v42, v16, v117
	v_and_b32_e32 v42, 0x7e, v42
	v_lshl_add_u32 v85, v42, 2, v129
	v_add_u32_e32 v42, v119, v26
	v_and_b32_e32 v42, 0x7e, v42
	v_lshl_add_u32 v86, v42, 2, v129
	v_add_u32_e32 v42, v16, v119
	v_and_b32_e32 v42, 0x7e, v42
	v_lshl_add_u32 v87, v42, 2, v129
	v_add_u32_e32 v42, v121, v26
	v_and_b32_e32 v42, 0x7e, v42
	v_lshl_add_u32 v88, v42, 2, v129
	v_add_u32_e32 v42, v16, v121
	v_and_b32_e32 v42, 0x7e, v42
	v_lshl_add_u32 v89, v42, 2, v129
	v_add_u32_e32 v42, v123, v26
	v_and_b32_e32 v42, 0x7e, v42
	v_lshl_add_u32 v90, v42, 2, v129
	v_add_u32_e32 v42, v16, v123
	v_and_b32_e32 v42, 0x7e, v42
	v_lshl_add_u32 v91, v42, 2, v129
	v_add_u32_e32 v42, v125, v26
	v_and_b32_e32 v42, 0x7e, v42
	v_lshl_add_u32 v92, v42, 2, v129
	v_add_u32_e32 v42, v16, v125
	v_and_b32_e32 v42, 0x7e, v42
	v_lshl_add_u32 v93, v42, 2, v129
	v_add_u32_e32 v42, v127, v26
	v_and_b32_e32 v42, 0x7e, v42
	v_add_u32_e32 v26, v130, v26
	v_lshl_add_u32 v94, v42, 2, v129
	v_add_u32_e32 v42, v16, v127
	v_and_b32_e32 v26, 0x7e, v26
	v_add_u32_e32 v16, v16, v130
	v_and_b32_e32 v42, 0x7e, v42
	v_lshl_add_u32 v96, v26, 2, v129
	v_and_b32_e32 v16, 0x7e, v16
	v_lshlrev_b32_e32 v26, 3, v99
	v_lshl_add_u32 v95, v42, 2, v129
	v_lshl_add_u32 v97, v16, 2, v129
	v_min_u32_e32 v16, 14, v98
	v_add_u32_e32 v42, v8, v26
	v_lshl_add_u32 v16, v16, 3, 8
	v_and_b32_e32 v42, 0x7e, v42
	v_lshl_add_u32 v98, v42, 2, v129
	v_add_u32_e32 v42, v16, v8
	v_and_b32_e32 v42, 0x7e, v42
	v_lshl_add_u32 v99, v42, 2, v129
	v_add_u32_e32 v42, v117, v26
	v_and_b32_e32 v42, 0x7e, v42
	v_lshl_add_u32 v100, v42, 2, v129
	v_add_u32_e32 v42, v16, v117
	v_and_b32_e32 v42, 0x7e, v42
	v_lshl_add_u32 v101, v42, 2, v129
	v_add_u32_e32 v42, v119, v26
	v_and_b32_e32 v42, 0x7e, v42
	v_lshl_add_u32 v102, v42, 2, v129
	v_add_u32_e32 v42, v16, v119
	v_and_b32_e32 v42, 0x7e, v42
	v_lshl_add_u32 v103, v42, 2, v129
	v_add_u32_e32 v42, v121, v26
	v_and_b32_e32 v42, 0x7e, v42
	v_lshl_add_u32 v104, v42, 2, v129
	v_add_u32_e32 v42, v16, v121
	v_and_b32_e32 v42, 0x7e, v42
	v_lshl_add_u32 v105, v42, 2, v129
	v_add_u32_e32 v42, v123, v26
	v_and_b32_e32 v42, 0x7e, v42
	v_lshl_add_u32 v106, v42, 2, v129
	v_add_u32_e32 v42, v16, v123
	v_and_b32_e32 v42, 0x7e, v42
	v_lshl_add_u32 v107, v42, 2, v129
	v_add_u32_e32 v42, v125, v26
	v_and_b32_e32 v42, 0x7e, v42
	v_lshl_add_u32 v108, v42, 2, v129
	v_add_u32_e32 v42, v16, v125
	v_and_b32_e32 v42, 0x7e, v42
	v_lshl_add_u32 v109, v42, 2, v129
	v_add_u32_e32 v42, v127, v26
	v_and_b32_e32 v42, 0x7e, v42
	v_lshl_add_u32 v110, v42, 2, v129
	v_add_u32_e32 v42, v16, v127
	v_add_u32_e32 v16, v16, v130
	v_add_u32_e32 v26, v130, v26
	v_and_b32_e32 v16, 0x7e, v16
	v_and_b32_e32 v26, 0x7e, v26
	v_lshl_add_u32 v113, v16, 2, v129
	v_min_u32_e32 v16, 14, v114
	v_lshlrev_b32_e32 v64, 3, v23
	v_and_b32_e32 v42, 0x7e, v42
	v_lshl_add_u32 v112, v26, 2, v129
	v_lshlrev_b32_e32 v26, 3, v115
	v_lshl_add_u32 v16, v16, 3, 8
	v_add_u32_e32 v50, v8, v64
	v_lshl_add_u32 v111, v42, 2, v129
	v_add_u32_e32 v42, v8, v26
	v_add_u32_e32 v8, v16, v8
	v_and_b32_e32 v8, 0x7e, v8
	v_lshl_add_u32 v115, v8, 2, v129
	v_add_u32_e32 v8, v117, v26
	v_and_b32_e32 v8, 0x7e, v8
	v_lshl_add_u32 v116, v8, 2, v129
	v_add_u32_e32 v8, v16, v117
	v_and_b32_e32 v8, 0x7e, v8
	v_add_u32_e32 v52, v117, v64
	v_lshl_add_u32 v117, v8, 2, v129
	v_add_u32_e32 v8, v119, v26
	v_and_b32_e32 v8, 0x7e, v8
	v_lshl_add_u32 v118, v8, 2, v129
	v_add_u32_e32 v8, v16, v119
	v_and_b32_e32 v8, 0x7e, v8
	v_add_u32_e32 v54, v119, v64
	v_lshl_add_u32 v119, v8, 2, v129
	v_add_u32_e32 v8, v121, v26
	v_and_b32_e32 v8, 0x7e, v8
	v_lshl_add_u32 v120, v8, 2, v129
	v_add_u32_e32 v8, v16, v121
	v_and_b32_e32 v8, 0x7e, v8
	v_add_u32_e32 v56, v121, v64
	v_lshl_add_u32 v121, v8, 2, v129
	v_add_u32_e32 v8, v123, v26
	v_and_b32_e32 v8, 0x7e, v8
	v_lshl_add_u32 v122, v8, 2, v129
	v_add_u32_e32 v8, v16, v123
	v_and_b32_e32 v8, 0x7e, v8
	v_add_u32_e32 v58, v123, v64
	v_lshl_add_u32 v123, v8, 2, v129
	v_add_u32_e32 v8, v125, v26
	v_and_b32_e32 v8, 0x7e, v8
	v_lshl_add_u32 v124, v8, 2, v129
	v_add_u32_e32 v8, v16, v125
	v_and_b32_e32 v8, 0x7e, v8
	v_add_u32_e32 v60, v125, v64
	v_lshl_add_u32 v125, v8, 2, v129
	v_add_u32_e32 v8, v127, v26
	v_and_b32_e32 v8, 0x7e, v8
	v_lshl_add_u32 v126, v8, 2, v129
	v_add_u32_e32 v8, v16, v127
	v_and_b32_e32 v8, 0x7e, v8
	v_add_u32_e32 v62, v127, v64
	v_lshl_add_u32 v127, v8, 2, v129
	v_add_u32_e32 v8, v130, v26
	v_and_b32_e32 v8, 0x7e, v8
	v_add_u32_e32 v64, v130, v64
	v_lshl_add_u32 v128, v8, 2, v129
	v_add_u32_e32 v8, v16, v130
	v_and_b32_e32 v50, 0x7e, v50
	v_and_b32_e32 v51, 0x7e, v51
	v_and_b32_e32 v52, 0x7e, v52
	v_and_b32_e32 v53, 0x7e, v53
	v_and_b32_e32 v54, 0x7e, v54
	v_and_b32_e32 v55, 0x7e, v55
	v_and_b32_e32 v56, 0x7e, v56
	v_and_b32_e32 v57, 0x7e, v57
	v_and_b32_e32 v58, 0x7e, v58
	v_and_b32_e32 v59, 0x7e, v59
	v_and_b32_e32 v60, 0x7e, v60
	v_and_b32_e32 v61, 0x7e, v61
	v_and_b32_e32 v62, 0x7e, v62
	v_and_b32_e32 v63, 0x7e, v63
	v_and_b32_e32 v64, 0x7e, v64
	v_and_b32_e32 v42, 0x7e, v42
	v_and_b32_e32 v8, 0x7e, v8
	v_lshl_add_u32 v50, v50, 2, v129
	v_lshl_add_u32 v51, v51, 2, v129
	v_lshl_add_u32 v52, v52, 2, v129
	v_lshl_add_u32 v53, v53, 2, v129
	v_lshl_add_u32 v54, v54, 2, v129
	v_lshl_add_u32 v55, v55, 2, v129
	v_lshl_add_u32 v56, v56, 2, v129
	v_lshl_add_u32 v57, v57, 2, v129
	v_lshl_add_u32 v58, v58, 2, v129
	v_lshl_add_u32 v59, v59, 2, v129
	v_lshl_add_u32 v60, v60, 2, v129
	v_lshl_add_u32 v61, v61, 2, v129
	v_lshl_add_u32 v62, v62, 2, v129
	v_lshl_add_u32 v63, v63, 2, v129
	v_lshl_add_u32 v64, v64, 2, v129
	v_lshl_add_u32 v114, v42, 2, v129
	v_lshl_add_u32 v129, v8, 2, v129
	v_mbcnt_lo_u32_b32 v8, -1, 0
	v_mbcnt_hi_u32_b32 v8, -1, v8
	v_and_b32_e32 v16, 64, v8
	v_lshlrev_b32_e32 v4, 3, v11
	v_cmp_eq_u32_e64 s[44:45], 0, v11
	v_xor_b32_e32 v11, 16, v8
	v_add_u32_e32 v16, 64, v16
	v_cmp_lt_i32_e32 vcc, v11, v16
	v_min_u32_e32 v44, 12, v23
	v_add_u32_e32 v9, 0xa00, v165
	v_cndmask_b32_e32 v11, v8, v11, vcc
	v_add_u32_e32 v10, 0xe00, v165
	v_lshl_or_b32 v44, v44, 4, v25
	v_lshlrev_b32_e32 v130, 2, v11
	v_xor_b32_e32 v11, 32, v8
	v_lshrrev_b32_e32 v9, 4, v9
	v_lshrrev_b32_e32 v10, 4, v10
	v_add_u32_e32 v17, 16, v17
	v_add_u32_e32 v44, 48, v44
	v_cmp_lt_i32_e32 vcc, v11, v16
	v_and_b32_e32 v2, 0x78, v18
	v_mov_b32_e32 v27, 0
	v_add_u32_e32 v30, 0xffffff80, v9
	v_add_u32_e32 v34, 0xffffff80, v10
	v_mul_u32_u24_e32 v7, 0x110, v24
	v_mul_u32_u24_e32 v9, 0x110, v9
	v_mul_u32_u24_e32 v10, 0x110, v10
	v_mul_u32_u24_e32 v15, 0x110, v20
	v_mul_u32_u24_e32 v17, 0x110, v17
	v_mul_u32_u24_e32 v43, 0x110, v43
	v_mul_u32_u24_e32 v44, 0x110, v44
	v_cndmask_b32_e32 v8, v8, v11, vcc
	v_or_b32_e32 v35, 0xffffff80, v24
	v_ashrrev_i32_e32 v1, 31, v28
	v_or_b32_e32 v32, 64, v24
	v_ashrrev_i32_e32 v19, 31, v36
	v_mov_b32_e32 v21, v27
	s_mov_b32 s55, 0
	v_cmp_ne_u32_e64 s[20:21], 15, v23
	v_lshlrev_b32_e32 v131, 2, v8
	v_lshlrev_b32_e32 v26, 1, v2
	v_lshlrev_b32_e32 v42, 1, v4
	v_add_u32_e32 v132, v3, v7
	v_add_u32_e32 v133, v3, v12
	v_add_u32_e32 v134, v3, v13
	v_add_u32_e32 v135, v3, v14
	v_add_u32_e32 v136, v3, v9
	v_add_u32_e32 v137, v3, v10
	s_mov_b32 s2, 0xffff0000
	v_add_u32_e32 v138, v5, v15
	v_add_u32_e32 v139, v5, v17
	v_add_u32_e32 v140, v5, v43
	v_add_u32_e32 v141, v5, v44
	v_add_u32_e32 v142, v5, v142
	v_add_u32_e32 v143, v5, v143
	v_add_u32_e32 v144, v5, v144
	v_add_u32_e32 v145, v5, v145
	v_add_u32_e32 v146, v5, v146
	v_lshlrev_b32_e32 v44, 1, v6
	v_mov_b32_e32 v147, 0xff800000
	v_mov_b32_e32 v148, 0x41b17218
	s_mov_b32 s3, s94
	s_branch .LBB0_464

.LBB0_541:
	s_nop 0
	v_readlane_b32 s94, v228, 16
	v_readlane_b32 s88, v228, 20
	s_nop 3
	v_writelane_b32 v228, s88, 6
	s_cmp_gt_i32 s87, 3
	s_cselect_b64 s[0:1], -1, 0
	s_and_b64 s[2:3], s[52:53], s[0:1]
	s_andn2_b64 vcc, exec, s[2:3]
	s_cbranch_vccnz .LBB0_609
	s_cmp_gt_i32 s86, -1
	s_mov_b64 s[4:5], -1
	s_cbranch_scc0 .LBB0_596
	s_waitcnt vmcnt(0)
	s_waitcnt vmcnt(0) lgkmcnt(0)
	s_barrier
	s_mov_b64 s[4:5], exec
	v_readlane_b32 s2, v228, 4
	v_readlane_b32 s3, v228, 5
	s_and_b64 s[2:3], s[4:5], s[2:3]
	s_mov_b64 exec, s[2:3]
	s_cbranch_execz .LBB0_595
	s_add_i32 s2, 0, 0x23fc0
	v_mov_b32_e32 v1, s2
	s_waitcnt vmcnt(0) expcnt(0) lgkmcnt(0)
	ds_read_b32 v3, v1
	s_add_i32 s2, 0, 0x23fc4
	v_mov_b32_e32 v1, s2
	ds_read_b32 v1, v1
	s_waitcnt lgkmcnt(1)
	v_cmp_ne_u32_e32 vcc, 0, v3
	s_cbranch_vccnz .LBB0_559
	s_add_u32 s6, s84, 0x30200
	s_addc_u32 s7, s85, 0
	s_add_u32 s8, s84, 0x30400
	s_addc_u32 s9, s85, 0
	s_add_u32 s10, s84, 0x30500
	s_addc_u32 s11, s85, 0
	s_add_u32 s12, s84, 0x30600
	s_addc_u32 s13, s85, 0
	s_add_u32 s14, s84, 0x30700
	s_addc_u32 s15, s85, 0
	s_add_u32 s16, s84, 0x30800
	s_addc_u32 s17, s85, 0
	s_add_u32 s18, s84, 0x30900
	s_addc_u32 s19, s85, 0
	s_add_u32 s20, s84, 0x30a00
	s_addc_u32 s21, s85, 0
	s_add_u32 s22, s84, 0x30b00
	s_addc_u32 s23, s85, 0
	s_add_u32 s24, s84, 0x30c00
	s_addc_u32 s25, s85, 0
	s_add_u32 s26, s84, 0x30d00
	s_addc_u32 s27, s85, 0
	s_add_u32 s28, s84, 0x30e00
	s_addc_u32 s29, s85, 0
	s_add_u32 s30, s84, 0x30f00
	s_addc_u32 s31, s85, 0
	s_add_u32 s34, s84, 0x31000
	s_addc_u32 s35, s85, 0
	s_add_u32 s36, s84, 0x31100
	s_addc_u32 s37, s85, 0
	s_add_u32 s38, s84, 0x31200
	v_readlane_b32 s2, v228, 0
	s_addc_u32 s39, s85, 0
	s_mul_i32 s2, s89, s2
	s_add_u32 s40, s84, 0x31300
	s_mul_i32 s2, s2, s88
	s_addc_u32 s41, s85, 0
	s_mov_b32 s3, 1
	v_mov_b32_e32 v17, 0
	s_branch .LBB0_547

.LBB0_687:
	s_cmp_lt_i32 s86, 5
	s_cselect_b64 s[2:3], -1, 0
	s_and_b64 s[0:1], s[2:3], s[0:1]
	v_writelane_b32 v228, s0, 18
	s_andn2_b64 vcc, exec, s[0:1]
	s_nop 0
	v_writelane_b32 v228, s1, 19
	s_cbranch_vccnz .LBB0_758
	s_mov_b32 s97, 0
	s_cmpk_lt_i32 s88, 0xa0
	s_cselect_b64 s[10:11], -1, 0
	s_and_b64 s[0:1], s[10:11], exec
	s_cselect_b32 s3, 0, 0x50
	s_cmp_eq_u32 s88, 0x100
	s_cselect_b32 s3, 0, s3
	s_cmp_lt_i32 s94, s3
	s_cselect_b64 s[0:1], -1, 0
	s_or_b64 s[4:5], s[10:11], s[0:1]
	v_and_b32_e32 v131, 63, v165
	v_and_b32_e32 v148, 15, v165
	v_lshrrev_b32_e32 v151, 2, v165
	v_lshrrev_b32_e32 v150, 3, v165
	v_bfe_u32 v149, v165, 4, 2
	s_andn2_b64 vcc, exec, s[4:5]
	v_and_b32_e32 v130, 48, v165
	s_cbranch_vccnz .LBB0_748
.Lp4_gemm_entry:
	s_add_u32 s2, s84, 0x200000
	s_addc_u32 s28, s85, 0
	s_cmpk_lt_i32 s94, 0x50
	s_cselect_b64 s[6:7], -1, 0
	s_cmpk_gt_i32 s94, 0x4f
	v_readfirstlane_b32 s12, v165
	s_cbranch_scc1 .LBB0_691
	s_sub_i32 s4, s94, 64
	s_lshr_b32 s4, s4, 2
	s_and_b32 s5, s94, 3
	s_and_b32 s9, s94, 1
	s_add_i32 s4, s4, 32
	s_add_i32 s5, s5, 50
	s_ashr_i32 s8, s94, 1
	s_or_b32 s9, s9, 48
	s_cmp_lt_i32 s94, 64
	s_cselect_b32 s4, s8, s4
	s_cselect_b32 s44, s9, s5
	s_ashr_i32 s5, s4, 31
	s_lshl_b64 s[8:9], s[4:5], 20
	s_add_u32 s22, s56, s8
	s_addc_u32 s23, s57, s9
	s_lshl_b32 s5, s44, 20
	s_add_u32 s24, s2, s5
	s_addc_u32 s25, s28, 0
	s_andn2_b64 vcc, exec, s[6:7]
	s_cbranch_vccz .LBB0_692
	s_branch .LBB0_747

.LBB0_748:
	s_cmp_lg_u32 s97, 0
	s_cbranch_scc1 .Lp2_gemm_ret
	s_sub_i32 s46, s94, s3
	s_cmpk_gt_i32 s46, 0x3ff
	s_cselect_b64 s[4:5], -1, 0
	s_or_b64 s[0:1], s[0:1], s[4:5]
	s_and_b64 vcc, exec, s[0:1]
	s_cbranch_vccnz .LBB0_758
	s_lshl_b32 s0, s46, 3
	s_lshl_b32 s1, s46, 6
	s_and_b32 s0, s0, 0xfffff800
	s_and_b32 s1, s1, 0x7c0
	s_or_b32 s0, s0, s1
	v_and_b32_e32 v115, 0x78, v150
	s_waitcnt vmcnt(0)
	v_add_u32_e32 v2, s0, v115
	s_waitcnt lgkmcnt(0)
	v_or_b32_e32 v10, 3, v2
	s_lshl_b32 s1, s46, 2
	v_ashrrev_i32_e32 v11, 31, v10
	v_lshlrev_b32_e32 v20, 1, v165
	s_and_b32 s1, s1, 0x380
	v_lshlrev_b64 v[10:11], 13, v[10:11]
	v_and_b32_e32 v114, 0x7e, v20
	s_mov_b32 s77, 0
	s_lshl_b32 s76, s1, 1
	v_lshl_add_u64 v[10:11], s[64:65], 0, v[10:11]
	v_mov_b32_e32 v117, 0
	v_lshlrev_b32_e32 v116, 1, v114
	v_lshl_add_u64 v[10:11], v[10:11], 0, s[76:77]
	v_lshl_add_u64 v[12:13], v[10:11], 0, v[116:117]
	v_or_b32_e32 v10, 4, v2
	v_ashrrev_i32_e32 v11, 31, v10
	v_lshlrev_b64 v[10:11], 13, v[10:11]
	v_lshl_add_u64 v[10:11], s[64:65], 0, v[10:11]
	v_lshl_add_u64 v[10:11], v[10:11], 0, s[76:77]
	v_lshl_add_u64 v[14:15], v[10:11], 0, v[116:117]
	v_or_b32_e32 v10, 5, v2
	v_ashrrev_i32_e32 v11, 31, v10
	v_lshlrev_b64 v[10:11], 13, v[10:11]
	v_lshl_add_u64 v[10:11], s[64:65], 0, v[10:11]
	v_lshl_add_u64 v[10:11], v[10:11], 0, s[76:77]
	v_lshl_add_u64 v[16:17], v[10:11], 0, v[116:117]
	v_or_b32_e32 v10, 6, v2
	v_ashrrev_i32_e32 v11, 31, v10
	v_lshlrev_b64 v[10:11], 13, v[10:11]
	v_lshl_add_u64 v[10:11], s[64:65], 0, v[10:11]
	v_ashrrev_i32_e32 v3, 31, v2
	v_lshl_add_u64 v[10:11], v[10:11], 0, s[76:77]
	v_and_b32_e32 v150, 62, v20
	v_lshlrev_b64 v[4:5], 13, v[2:3]
	v_or_b32_e32 v6, 1, v2
	v_or_b32_e32 v8, 2, v2
	v_lshl_add_u64 v[18:19], v[10:11], 0, v[116:117]
	v_or_b32_e32 v2, 7, v2
	v_or_b32_e32 v10, s0, v150
	v_ashrrev_i32_e32 v7, 31, v6
	v_ashrrev_i32_e32 v9, 31, v8
	v_ashrrev_i32_e32 v3, 31, v2
	v_ashrrev_i32_e32 v11, 31, v10
	v_lshlrev_b64 v[6:7], 13, v[6:7]
	v_lshlrev_b64 v[8:9], 13, v[8:9]
	v_lshlrev_b64 v[2:3], 13, v[2:3]
	v_lshlrev_b64 v[10:11], 13, v[10:11]
	v_lshrrev_b32_e32 v43, 6, v165
	v_lshl_add_u64 v[4:5], s[64:65], 0, v[4:5]
	v_lshl_add_u64 v[6:7], s[64:65], 0, v[6:7]
	v_lshl_add_u64 v[8:9], s[64:65], 0, v[8:9]
	v_lshl_add_u64 v[2:3], s[64:65], 0, v[2:3]
	v_lshl_add_u64 v[10:11], s[64:65], 0, v[10:11]
	v_and_b32_e32 v41, 0xc0, v151
	s_sub_i32 s74, s88, s3
	v_and_or_b32 v1, v151, 48, v148
	v_lshl_add_u64 v[4:5], v[4:5], 0, s[76:77]
	v_lshl_add_u64 v[6:7], v[6:7], 0, s[76:77]
	v_lshl_add_u64 v[8:9], v[8:9], 0, s[76:77]
	v_lshl_add_u64 v[2:3], v[2:3], 0, s[76:77]
	v_lshl_add_u64 v[20:21], v[10:11], 0, s[76:77]
	v_and_b32_e32 v10, 0xf8, v151
	v_lshlrev_b32_e32 v151, 3, v43
	v_lshl_add_u64 v[4:5], v[4:5], 0, v[116:117]
	v_lshl_add_u64 v[6:7], v[6:7], 0, v[116:117]
	v_lshl_add_u64 v[8:9], v[8:9], 0, v[116:117]
	v_lshl_add_u64 v[2:3], v[2:3], 0, v[116:117]
	v_lshlrev_b32_e32 v116, 1, v10
	v_add_u32_e32 v22, s0, v151
	s_add_u32 s0, s64, s76
	v_lshl_add_u64 v[20:21], v[20:21], 0, v[116:117]
	v_or_b32_e32 v11, s1, v114
	s_addc_u32 s1, s65, 0
	v_lshlrev_b32_e32 v116, 2, v131
	v_lshl_add_u64 v[24:25], s[0:1], 0, v[116:117]
	s_add_i32 s0, 0, 0x12600
	v_lshl_add_u32 v152, v1, 2, s0
	s_add_i32 s0, 0, 0x11400
	v_lshl_add_u32 v154, v114, 2, s0
	s_movk_i32 s0, 0x7f
	v_cmp_lt_u32_e64 s[4:5], s0, v165
	s_movk_i32 s0, 0xbf
	v_cmp_lt_u32_e64 s[6:7], s0, v165
	s_movk_i32 s0, 0xff
	v_ashrrev_i32_e32 v23, 31, v22
	v_cmp_lt_u32_e64 s[8:9], s0, v165
	s_movk_i32 s0, 0x13f
	v_lshlrev_b64 v[26:27], 13, v[22:23]
	v_or_b32_e32 v28, 1, v22
	v_or_b32_e32 v30, 2, v22
	v_or_b32_e32 v32, 3, v22
	v_or_b32_e32 v34, 4, v22
	v_or_b32_e32 v36, 5, v22
	v_or_b32_e32 v38, 6, v22
	v_or_b32_e32 v22, 7, v22
	v_cmp_lt_u32_e64 s[10:11], s0, v165
	s_movk_i32 s0, 0x17f
	v_ashrrev_i32_e32 v29, 31, v28
	v_ashrrev_i32_e32 v31, 31, v30
	v_ashrrev_i32_e32 v33, 31, v32
	v_ashrrev_i32_e32 v35, 31, v34
	v_ashrrev_i32_e32 v37, 31, v36
	v_ashrrev_i32_e32 v39, 31, v38
	v_ashrrev_i32_e32 v23, 31, v22
	v_cmp_lt_u32_e64 s[12:13], s0, v165
	s_movk_i32 s0, 0x1bf
	v_lshlrev_b64 v[28:29], 13, v[28:29]
	v_lshlrev_b64 v[30:31], 13, v[30:31]
	v_lshlrev_b64 v[32:33], 13, v[32:33]
	v_lshlrev_b64 v[34:35], 13, v[34:35]
	v_lshlrev_b64 v[36:37], 13, v[36:37]
	v_lshlrev_b64 v[38:39], 13, v[38:39]
	v_lshlrev_b64 v[22:23], 13, v[22:23]
	v_cmp_lt_u32_e64 s[14:15], s0, v165
	s_movk_i32 s0, 0x1ff
	v_lshl_add_u64 v[26:27], v[24:25], 0, v[26:27]
	v_lshl_add_u64 v[28:29], v[24:25], 0, v[28:29]
	v_lshl_add_u64 v[30:31], v[24:25], 0, v[30:31]
	v_lshl_add_u64 v[32:33], v[24:25], 0, v[32:33]
	v_lshl_add_u64 v[34:35], v[24:25], 0, v[34:35]
	v_lshl_add_u64 v[36:37], v[24:25], 0, v[36:37]
	v_lshl_add_u64 v[38:39], v[24:25], 0, v[38:39]
	v_lshl_add_u64 v[22:23], v[24:25], 0, v[22:23]
	v_and_b32_e32 v24, 31, v165
	v_cmp_lt_u32_e64 s[16:17], s0, v165
	s_add_i32 s0, 0, 0x12400
	v_mul_u32_u24_e32 v25, 0x90, v10
	v_lshlrev_b32_e32 v24, 2, v24
	v_lshl_add_u32 v156, v131, 3, s0
	s_movk_i32 s0, 0x110
	v_add3_u32 v153, 0, v25, v24
	v_mad_u32_u24 v25, v1, s0, 0
	s_movk_i32 s0, 0x220
	v_cmp_eq_u32_e64 s[18:19], 4, v43
	v_mad_u32_u24 v43, v43, s0, v131
	s_movk_i32 s0, 0x1000
	global_load_dword v160, v[4:5], off offset:2048
	global_load_dword v161, v[6:7], off offset:2048
	global_load_dword v162, v[8:9], off offset:2048
	global_load_dword v163, v[12:13], off offset:2048
	global_load_dword v164, v[14:15], off offset:2048
	global_load_dword v166, v[16:17], off offset:2048
	global_load_dword v167, v[18:19], off offset:2048
	global_load_dword v174, v[2:3], off offset:2048
	v_add_co_u32_e64 v2, s[0:1], s0, v20
	v_lshlrev_b32_e32 v11, 2, v11
	s_nop 0
	v_addc_co_u32_e64 v3, s[0:1], 0, v21, s[0:1]
	s_movk_i32 s0, 0x3000
	s_nop 0
	v_add_co_u32_e64 v4, s[0:1], s0, v20
	s_lshl_b32 s33, s3, 7
	s_nop 0
	v_addc_co_u32_e64 v5, s[0:1], 0, v21, s[0:1]
	global_load_dwordx4 v[6:9], v[4:5], off
	global_load_dwordx2 v[140:141], v11, s[90:91]
	global_load_dword v139, v[26:27], off
	global_load_dword v175, v[28:29], off
	global_load_dword v176, v[30:31], off
	global_load_dword v177, v[32:33], off
	global_load_dword v178, v[34:35], off
	global_load_dword v179, v[36:37], off
	global_load_dword v180, v[38:39], off
	s_nop 0
	global_load_dwordx4 v[2:5], v[2:3], off
	s_nop 0
	global_load_dword v181, v[22:23], off
	s_lshl_b32 s0, s88, 3
	s_lshl_b32 s1, s3, 4
	s_sub_i32 s2, s0, s1
	s_lshl_b32 s1, s3, 3
	s_sub_i32 s96, s0, s1
	s_lshl_b32 s0, s88, 6
	s_lshl_b32 s48, s3, 6
	v_lshlrev_b32_e32 v42, 2, v149
	v_lshl_add_u32 v157, v43, 2, 0
	v_mul_u32_u24_e32 v43, 0x110, v148
	s_sub_i32 s97, s0, s33
	s_sub_i32 s72, s0, s48
	s_lshl_b32 s0, s88, 2
	s_lshl_b32 s47, s3, 2
	v_add3_u32 v158, 0, v130, v43
	v_or_b32_e32 v43, 2, v42
	s_sub_i32 s73, s0, s1
	s_sub_i32 s93, s0, s47
	s_lshl_b32 s0, s3, 1
	v_lshlrev_b32_e32 v18, 6, v165
	v_lshlrev_b32_e32 v24, 3, v165
	v_cmp_gt_u32_e64 s[26:27], v43, v1
	v_or_b32_e32 v43, 3, v42
	s_sub_i32 s66, s88, s0
	s_sub_i32 s67, 0, s47
	v_lshlrev_b32_e32 v17, 8, v148
	v_and_b32_e32 v18, 0xc000, v18
	s_mov_b32 s0, 0xd000080
	s_ashr_i32 s47, s46, 31
	v_and_b32_e32 v24, 0x1e00, v24
	v_cmp_gt_u32_e64 s[28:29], v43, v1
	v_or_b32_e32 v43, 16, v42
	v_or_b32_e32 v11, 32, v42
	s_lshl_b32 s91, s94, 3
	s_lshl_b32 s33, s94, 6
	s_lshl_b32 s92, s94, 2
	s_sub_i32 s3, 0, s3
	s_sub_i32 s78, 0, s1
	v_or3_b32 v124, v18, v17, s0
	s_lshl_b64 s[0:1], s[46:47], 15
	v_add_u32_e32 v155, v154, v24
	v_or_b32_e32 v24, v42, v41
	v_cmp_gt_u32_e64 s[30:31], v43, v1
	v_or_b32_e32 v43, 17, v42
	v_cmp_gt_u32_e64 s[40:41], v11, v1
	v_or_b32_e32 v11, 33, v42
	s_add_u32 s0, s84, s0
	v_lshl_add_u64 v[118:119], s[64:65], 0, v[116:117]
	v_or_b32_e32 v44, v41, v148
	v_cmp_gt_u32_e64 s[20:21], 16, v131
	v_lshlrev_b32_e32 v116, 2, v24
	v_add_u32_e32 v40, v41, v42
	v_cmp_gt_u32_e64 s[34:35], v43, v1
	v_or_b32_e32 v43, 18, v42
	v_cmp_gt_u32_e64 s[42:43], v11, v1
	v_or_b32_e32 v11, 34, v42
	v_mov_b32_e32 v131, v117
	s_addc_u32 s1, s85, s1
	s_mov_b32 s46, s94
	v_lshl_add_u32 v45, v149, 3, 0
	v_and_b32_e32 v46, 0x300, v165
	v_lshl_add_u64 v[120:121], s[68:69], 0, v[116:117]
	v_lshlrev_b32_e32 v116, 2, v40
	v_cmp_gt_u32_e64 s[36:37], v43, v1
	v_or_b32_e32 v43, 19, v42
	v_cmp_gt_u32_e64 s[44:45], v11, v1
	v_or_b32_e32 v11, 35, v42
	v_or_b32_e32 v12, 48, v42
	v_or_b32_e32 v13, 49, v42
	v_or_b32_e32 v14, 50, v42
	v_or_b32_e32 v15, 51, v42
	v_mul_u32_u24_e32 v16, 0x90, v44
	v_lshl_add_u64 v[126:127], s[0:1], 0, v[130:131]
	s_ashr_i32 s75, s74, 31
	v_add_lshl_u32 v17, v41, v148, 8
	v_lshlrev_b32_e32 v138, 1, v10
	v_mbcnt_lo_u32_b32 v10, -1, 0
	s_mov_b32 s0, s46
	v_cmp_gt_u32_e32 vcc, 64, v165
	v_lshl_add_u64 v[122:123], s[68:69], 0, v[116:117]
	v_add_u32_e32 v159, 0xd000, v158
	v_cmp_gt_u32_e64 s[22:23], v42, v1
	v_cmp_lt_u32_e64 s[24:25], v42, v1
	v_cmp_gt_u32_e64 s[38:39], v43, v1
	v_mov_b32_e32 v125, v117
	s_sub_i32 s79, 0, s48
	v_add_u32_e32 v128, 0xd003080, v17
	v_mov_b32_e32 v129, v117
	v_add_u32_e32 v132, 0xd002080, v17
	v_mov_b32_e32 v133, v117
	v_add_u32_e32 v134, 0xd001080, v17
	v_mov_b32_e32 v135, v117
	v_lshlrev_b32_e32 v116, 1, v24
	v_lshlrev_b32_e32 v136, 1, v40
	s_mov_b32 s94, 0xffff0000
	s_mov_b32 s95, 0x800000
	s_mov_b32 s88, 0x3f317217
	s_mov_b32 s89, 0x7f800000
	v_add_u32_e32 v168, v25, v130
	v_add_u32_e32 v169, v45, v16
	v_mbcnt_hi_u32_b32 v170, -1, v10
	v_add_u32_e32 v171, v152, v46
	v_mov_b32_e32 v172, 0x358637bd
	v_mov_b32_e32 v173, 0x41b17218
	v_writelane_b32 v228, s0, 16
	s_mov_b32 s90, s46
	v_cmp_gt_u32_e64 s[46:47], v11, v1
	v_cmp_gt_u32_e64 s[48:49], v12, v1
	v_cmp_gt_u32_e64 s[50:51], v13, v1
	v_cmp_gt_u32_e64 s[52:53], v14, v1
	v_cmp_gt_u32_e64 s[54:55], v15, v1
	s_lshl_b64 s[68:69], s[74:75], 15
	s_movk_i32 s75, 0x1000
	v_writelane_b32 v228, s1, 17
	s_branch .LBB0_751
